# own: nsel-dispatched counted waits so partial-result loads stream during tile compute; (m,l) loads split to avoid copy drains
# speedup vs baseline: 1.0219x; 1.0065x over previous
.LBB0_277:
	s_ashr_i32 s0, s23, 7
	s_ashr_i32 s1, s0, 31
	s_lshl_b64 s[0:1], s[0:1], 22
	s_waitcnt vmcnt(0)
	v_lshlrev_b32_e32 v20, 10, v140
	v_mov_b32_e32 v21, v121
	v_lshl_add_u64 v[20:21], s[0:1], 0, v[20:21]
	v_lshlrev_b64 v[20:21], 1, v[20:21]
	s_lshl_b32 s0, s14, 7
	v_lshl_add_u64 v[22:23], s[70:71], 0, v[20:21]
	s_and_b32 s12, s0, 0x380
	v_lshl_add_u64 v[22:23], v[22:23], 0, s[12:13]
	v_mov_b32_e32 v75, v121
	v_lshl_add_u64 v[140:141], v[22:23], 0, v[74:75]
	s_mov_b64 s[72:73], 0x8000
	global_load_dwordx2 v[234:235], v[140:141], off offset:1024
	global_load_dwordx2 v[236:237], v[140:141], off offset:1056
	global_load_dwordx2 v[238:239], v[140:141], off offset:1088
	global_load_dwordx2 v[240:241], v[140:141], off offset:1120
	v_lshl_add_u64 v[250:251], v[140:141], 0, s[72:73]
	global_load_dwordx2 v[242:243], v[250:251], off offset:1024
	global_load_dwordx2 v[244:245], v[250:251], off offset:1056
	global_load_dwordx2 v[246:247], v[250:251], off offset:1088
	global_load_dwordx2 v[248:249], v[250:251], off offset:1120
	v_max_f32_e32 v22, v132, v132
	v_max_f32_e32 v23, v71, v71
	s_waitcnt vmcnt(9)
	v_max_f32_e32 v30, v23, v22
	v_sub_f32_e32 v22, v71, v30
	v_sub_f32_e32 v23, v132, v30
	v_exp_f32_e32 v22, v22
	v_exp_f32_e32 v23, v23
	v_max_f32_e32 v24, v148, v148
	v_max_f32_e32 v24, v30, v24
	v_mov_b32_e32 v132, v114
	v_sub_f32_e32 v30, v30, v24
	v_exp_f32_e32 v139, v30
	v_pk_mul_f32 v[30:31], v[132:133], v[22:23]
	v_sub_f32_e32 v65, v148, v24
	v_pk_fma_f32 v[132:133], v[132:133], v[22:23], v[30:31] op_sel_hi:[1,1,0]
	v_lshlrev_b32_e32 v26, 16, v142
	v_exp_f32_e32 v132, v65
	v_and_b32_e32 v27, 0xffff0000, v142
	v_lshlrev_b32_e32 v28, 16, v143
	v_and_b32_e32 v29, 0xffff0000, v143
	v_max_f32_e32 v25, v152, v152
	s_waitcnt vmcnt(8)
	v_pk_mul_f32 v[32:33], v[30:31], v[26:27] op_sel:[1,0]
	v_max_f32_e32 v25, v24, v25
	v_mov_b32_e32 v26, v139
	v_pk_mul_f32 v[148:149], v[30:31], v[28:29] op_sel:[1,0]
	v_pk_fma_f32 v[32:33], v[44:45], v[22:23], v[32:33] op_sel_hi:[1,0,1]
	v_sub_f32_e32 v24, v24, v25
	v_pk_fma_f32 v[44:45], v[46:47], v[22:23], v[148:149] op_sel_hi:[1,0,1]
	v_pk_mul_f32 v[46:47], v[26:27], v[32:33] op_sel_hi:[0,1]
	v_pk_mul_f32 v[32:33], v[138:139], v[132:133]
	v_sub_f32_e32 v67, v152, v25
	v_exp_f32_e32 v137, v24
	v_pk_fma_f32 v[132:133], v[138:139], v[132:133], v[32:33] op_sel_hi:[1,1,0]
	v_lshlrev_b32_e32 v34, 16, v150
	v_exp_f32_e32 v132, v67
	v_and_b32_e32 v35, 0xffff0000, v150
	v_mov_b32_e32 v28, v137
	v_pk_fma_f32 v[34:35], v[32:33], v[34:35], v[46:47] op_sel_hi:[0,1,1]
	v_pk_mul_f32 v[138:139], v[28:29], v[34:35] op_sel_hi:[0,1]
	v_pk_mul_f32 v[34:35], v[136:137], v[132:133]
	v_lshlrev_b32_e32 v142, 16, v151
	v_and_b32_e32 v143, 0xffff0000, v151
	v_pk_mul_f32 v[44:45], v[26:27], v[44:45] op_sel_hi:[0,1]
	v_add_f32_e32 v23, v34, v35
	v_pk_fma_f32 v[46:47], v[32:33], v[142:143], v[44:45] op_sel_hi:[0,1,1]
	v_rcp_f32_e32 v44, v23
	v_lshlrev_b32_e32 v150, 16, v154
	v_and_b32_e32 v151, 0xffff0000, v154
	v_lshlrev_b32_e32 v154, 16, v155
	v_and_b32_e32 v155, 0xffff0000, v155
	v_pk_mul_f32 v[46:47], v[28:29], v[46:47] op_sel_hi:[0,1]
	v_pk_fma_f32 v[132:133], v[34:35], v[150:151], v[138:139] op_sel_hi:[0,1,1]
	v_pk_fma_f32 v[46:47], v[34:35], v[154:155], v[46:47] op_sel_hi:[0,1,1]
	v_pk_mul_f32 v[132:133], v[44:45], v[132:133] op_sel_hi:[0,1]
	v_pk_mul_f32 v[46:47], v[44:45], v[46:47] op_sel_hi:[0,1]
	v_readlane_b32 s16, v254, 2
	v_readlane_b32 s17, v254, 3
	s_add_i32 s23, s23, s3
	s_cmpk_lt_i32 s23, 0x800
	v_lshl_add_u64 v[24:25], s[16:17], 0, v[20:21]
	v_lshl_add_u64 v[24:25], v[24:25], 0, s[12:13]
	v_lshl_add_u64 v[24:25], v[24:25], 0, v[74:75]
	v_or_b32_e32 v20, 0x8000, v20
	v_readlane_b32 s18, v254, 4
	v_readlane_b32 s19, v254, 5
	s_waitcnt vmcnt(7)
	v_mov_b32_e32 v156, v234
	v_mov_b32_e32 v157, v235
	v_lshlrev_b32_e32 v136, 16, v156
	v_and_b32_e32 v137, 0xffff0000, v156
	v_lshlrev_b32_e32 v138, 16, v157
	v_and_b32_e32 v139, 0xffff0000, v157
	v_mul_f32_e32 v23, 0xbfb8aa3b, v136
	v_mul_f32_e32 v27, 0xbfb8aa3b, v137
	v_mul_f32_e32 v29, 0xbfb8aa3b, v138
	v_mul_f32_e32 v45, 0xbfb8aa3b, v139
	v_exp_f32_e32 v23, v23
	v_exp_f32_e32 v27, v27
	v_exp_f32_e32 v29, v29
	v_exp_f32_e32 v45, v45
	v_add_f32_e32 v23, 1.0, v23
	v_add_f32_e32 v27, 1.0, v27
	v_add_f32_e32 v29, 1.0, v29
	v_add_f32_e32 v45, 1.0, v45
	v_rcp_f32_e32 v142, v23
	v_rcp_f32_e32 v143, v27
	v_rcp_f32_e32 v148, v29
	v_rcp_f32_e32 v149, v45
	v_pk_mul_f32 v[132:133], v[132:133], v[136:137]
	v_pk_mul_f32 v[46:47], v[46:47], v[138:139]
	v_pk_mul_f32 v[132:133], v[132:133], v[142:143]
	v_pk_mul_f32 v[46:47], v[46:47], v[148:149]
	v_cvt_pk_bf16_f32 v132, v132, v133
	v_cvt_pk_bf16_f32 v133, v46, v47
	global_store_dwordx2 v[24:25], v[132:133], off offset:1024
	v_lshlrev_b32_e32 v132, 16, v128
	v_and_b32_e32 v133, 0xffff0000, v128
	v_lshlrev_b32_e32 v128, 16, v129
	v_and_b32_e32 v129, 0xffff0000, v129
	v_pk_mul_f32 v[132:133], v[30:31], v[132:133] op_sel:[1,0]
	v_pk_mul_f32 v[128:129], v[30:31], v[128:129] op_sel:[1,0]
	v_pk_fma_f32 v[40:41], v[40:41], v[22:23], v[132:133] op_sel_hi:[1,0,1]
	v_pk_fma_f32 v[42:43], v[42:43], v[22:23], v[128:129] op_sel_hi:[1,0,1]
	v_lshlrev_b32_e32 v136, 16, v130
	v_and_b32_e32 v137, 0xffff0000, v130
	v_lshlrev_b32_e32 v130, 16, v131
	v_and_b32_e32 v131, 0xffff0000, v131
	v_pk_mul_f32 v[40:41], v[26:27], v[40:41] op_sel_hi:[0,1]
	v_pk_mul_f32 v[42:43], v[26:27], v[42:43] op_sel_hi:[0,1]
	v_pk_fma_f32 v[40:41], v[32:33], v[136:137], v[40:41] op_sel_hi:[0,1,1]
	v_pk_fma_f32 v[42:43], v[32:33], v[130:131], v[42:43] op_sel_hi:[0,1,1]
	v_lshlrev_b32_e32 v138, 16, v134
	v_and_b32_e32 v139, 0xffff0000, v134
	v_lshlrev_b32_e32 v134, 16, v135
	v_and_b32_e32 v135, 0xffff0000, v135
	v_pk_mul_f32 v[40:41], v[28:29], v[40:41] op_sel_hi:[0,1]
	v_pk_mul_f32 v[42:43], v[28:29], v[42:43] op_sel_hi:[0,1]
	v_pk_fma_f32 v[40:41], v[34:35], v[138:139], v[40:41] op_sel_hi:[0,1,1]
	v_pk_fma_f32 v[42:43], v[34:35], v[134:135], v[42:43] op_sel_hi:[0,1,1]
	v_pk_mul_f32 v[40:41], v[44:45], v[40:41] op_sel_hi:[0,1]
	v_pk_mul_f32 v[42:43], v[44:45], v[42:43] op_sel_hi:[0,1]
	s_waitcnt vmcnt(7)
	v_mov_b32_e32 v46, v236
	v_mov_b32_e32 v47, v237
	v_lshlrev_b32_e32 v128, 16, v46
	v_and_b32_e32 v129, 0xffff0000, v46
	v_lshlrev_b32_e32 v46, 16, v47
	v_and_b32_e32 v47, 0xffff0000, v47
	v_mul_f32_e32 v23, 0xbfb8aa3b, v128
	v_mul_f32_e32 v27, 0xbfb8aa3b, v129
	v_mul_f32_e32 v29, 0xbfb8aa3b, v46
	v_mul_f32_e32 v45, 0xbfb8aa3b, v47
	v_exp_f32_e32 v23, v23
	v_exp_f32_e32 v27, v27
	v_exp_f32_e32 v29, v29
	v_exp_f32_e32 v45, v45
	v_add_f32_e32 v23, 1.0, v23
	v_add_f32_e32 v27, 1.0, v27
	v_add_f32_e32 v29, 1.0, v29
	v_add_f32_e32 v45, 1.0, v45
	v_rcp_f32_e32 v130, v23
	v_rcp_f32_e32 v131, v27
	v_rcp_f32_e32 v132, v29
	v_rcp_f32_e32 v133, v45
	v_pk_mul_f32 v[40:41], v[40:41], v[128:129]
	v_pk_mul_f32 v[42:43], v[42:43], v[46:47]
	v_pk_mul_f32 v[40:41], v[40:41], v[130:131]
	v_pk_mul_f32 v[42:43], v[42:43], v[132:133]
	v_cvt_pk_bf16_f32 v40, v40, v41
	v_cvt_pk_bf16_f32 v41, v42, v43
	global_store_dwordx2 v[24:25], v[40:41], off offset:1056
	v_lshlrev_b32_e32 v42, 16, v118
	v_and_b32_e32 v43, 0xffff0000, v118
	v_lshlrev_b32_e32 v46, 16, v119
	v_and_b32_e32 v47, 0xffff0000, v119
	v_pk_mul_f32 v[42:43], v[30:31], v[42:43] op_sel:[1,0]
	v_pk_mul_f32 v[46:47], v[30:31], v[46:47] op_sel:[1,0]
	v_pk_fma_f32 v[36:37], v[36:37], v[22:23], v[42:43] op_sel_hi:[1,0,1]
	v_pk_fma_f32 v[38:39], v[38:39], v[22:23], v[46:47] op_sel_hi:[1,0,1]
	v_lshlrev_b32_e32 v118, 16, v124
	v_and_b32_e32 v119, 0xffff0000, v124
	v_lshlrev_b32_e32 v124, 16, v125
	v_and_b32_e32 v125, 0xffff0000, v125
	v_pk_mul_f32 v[36:37], v[26:27], v[36:37] op_sel_hi:[0,1]
	v_pk_mul_f32 v[38:39], v[26:27], v[38:39] op_sel_hi:[0,1]
	v_pk_fma_f32 v[36:37], v[32:33], v[118:119], v[36:37] op_sel_hi:[0,1,1]
	v_pk_fma_f32 v[38:39], v[32:33], v[124:125], v[38:39] op_sel_hi:[0,1,1]
	v_lshlrev_b32_e32 v128, 16, v126
	v_and_b32_e32 v129, 0xffff0000, v126
	v_lshlrev_b32_e32 v126, 16, v127
	v_and_b32_e32 v127, 0xffff0000, v127
	v_pk_mul_f32 v[36:37], v[28:29], v[36:37] op_sel_hi:[0,1]
	v_pk_mul_f32 v[38:39], v[28:29], v[38:39] op_sel_hi:[0,1]
	v_pk_fma_f32 v[36:37], v[34:35], v[128:129], v[36:37] op_sel_hi:[0,1,1]
	v_pk_fma_f32 v[38:39], v[34:35], v[126:127], v[38:39] op_sel_hi:[0,1,1]
	v_pk_mul_f32 v[36:37], v[44:45], v[36:37] op_sel_hi:[0,1]
	v_pk_mul_f32 v[38:39], v[44:45], v[38:39] op_sel_hi:[0,1]
	s_waitcnt vmcnt(7)
	v_mov_b32_e32 v40, v238
	v_mov_b32_e32 v41, v239
	v_lshlrev_b32_e32 v42, 16, v40
	v_and_b32_e32 v43, 0xffff0000, v40
	v_lshlrev_b32_e32 v40, 16, v41
	v_and_b32_e32 v41, 0xffff0000, v41
	v_mul_f32_e32 v23, 0xbfb8aa3b, v42
	v_mul_f32_e32 v27, 0xbfb8aa3b, v43
	v_mul_f32_e32 v29, 0xbfb8aa3b, v40
	v_mul_f32_e32 v45, 0xbfb8aa3b, v41
	v_exp_f32_e32 v23, v23
	v_exp_f32_e32 v27, v27
	v_exp_f32_e32 v29, v29
	v_exp_f32_e32 v45, v45
	v_add_f32_e32 v23, 1.0, v23
	v_add_f32_e32 v27, 1.0, v27
	v_add_f32_e32 v29, 1.0, v29
	v_add_f32_e32 v45, 1.0, v45
	v_rcp_f32_e32 v46, v23
	v_rcp_f32_e32 v47, v27
	v_rcp_f32_e32 v118, v29
	v_rcp_f32_e32 v119, v45
	v_pk_mul_f32 v[36:37], v[36:37], v[42:43]
	v_pk_mul_f32 v[38:39], v[38:39], v[40:41]
	v_pk_mul_f32 v[36:37], v[36:37], v[46:47]
	v_pk_mul_f32 v[38:39], v[38:39], v[118:119]
	v_cvt_pk_bf16_f32 v36, v36, v37
	v_cvt_pk_bf16_f32 v37, v38, v39
	global_store_dwordx2 v[24:25], v[36:37], off offset:1088
	v_lshlrev_b32_e32 v38, 16, v112
	v_and_b32_e32 v39, 0xffff0000, v112
	v_lshlrev_b32_e32 v40, 16, v113
	v_and_b32_e32 v41, 0xffff0000, v113
	v_pk_mul_f32 v[38:39], v[30:31], v[38:39] op_sel:[1,0]
	v_pk_mul_f32 v[40:41], v[30:31], v[40:41] op_sel:[1,0]
	v_pk_fma_f32 v[16:17], v[16:17], v[22:23], v[38:39] op_sel_hi:[1,0,1]
	v_pk_fma_f32 v[18:19], v[18:19], v[22:23], v[40:41] op_sel_hi:[1,0,1]
	v_lshlrev_b32_e32 v42, 16, v110
	v_and_b32_e32 v43, 0xffff0000, v110
	v_lshlrev_b32_e32 v46, 16, v111
	v_and_b32_e32 v47, 0xffff0000, v111
	v_pk_mul_f32 v[16:17], v[26:27], v[16:17] op_sel_hi:[0,1]
	v_pk_mul_f32 v[18:19], v[26:27], v[18:19] op_sel_hi:[0,1]
	v_pk_fma_f32 v[16:17], v[32:33], v[42:43], v[16:17] op_sel_hi:[0,1,1]
	v_pk_fma_f32 v[18:19], v[32:33], v[46:47], v[18:19] op_sel_hi:[0,1,1]
	v_pk_mul_f32 v[16:17], v[28:29], v[16:17] op_sel_hi:[0,1]
	v_pk_mul_f32 v[18:19], v[28:29], v[18:19] op_sel_hi:[0,1]
	v_lshlrev_b32_e32 v110, 16, v116
	v_and_b32_e32 v111, 0xffff0000, v116
	v_lshlrev_b32_e32 v112, 16, v117
	v_and_b32_e32 v113, 0xffff0000, v117
	v_pk_fma_f32 v[16:17], v[34:35], v[110:111], v[16:17] op_sel_hi:[0,1,1]
	v_pk_fma_f32 v[18:19], v[34:35], v[112:113], v[18:19] op_sel_hi:[0,1,1]
	v_pk_mul_f32 v[16:17], v[44:45], v[16:17] op_sel_hi:[0,1]
	v_pk_mul_f32 v[18:19], v[44:45], v[18:19] op_sel_hi:[0,1]
	v_lshl_add_u64 v[116:117], s[70:71], 0, v[20:21]
	v_lshl_add_u64 v[116:117], v[116:117], 0, s[12:13]
	v_lshl_add_u64 v[30:31], v[116:117], 0, v[74:75]
	v_lshlrev_b32_e32 v34, 16, v108
	v_and_b32_e32 v35, 0xffff0000, v108
	s_waitcnt vmcnt(7)
	v_mov_b32_e32 v36, v240
	v_mov_b32_e32 v37, v241
	v_lshlrev_b32_e32 v22, 16, v36
	v_and_b32_e32 v23, 0xffff0000, v36
	v_lshlrev_b32_e32 v26, 16, v37
	v_and_b32_e32 v27, 0xffff0000, v37
	v_mul_f32_e32 v28, 0xbfb8aa3b, v22
	v_mul_f32_e32 v29, 0xbfb8aa3b, v23
	v_mul_f32_e32 v32, 0xbfb8aa3b, v26
	v_mul_f32_e32 v33, 0xbfb8aa3b, v27
	v_exp_f32_e32 v28, v28
	v_exp_f32_e32 v29, v29
	v_exp_f32_e32 v32, v32
	v_exp_f32_e32 v33, v33
	v_add_f32_e32 v28, 1.0, v28
	v_add_f32_e32 v29, 1.0, v29
	v_add_f32_e32 v32, 1.0, v32
	v_add_f32_e32 v33, 1.0, v33
	v_rcp_f32_e32 v28, v28
	v_rcp_f32_e32 v29, v29
	v_rcp_f32_e32 v32, v32
	v_rcp_f32_e32 v33, v33
	v_pk_mul_f32 v[16:17], v[16:17], v[22:23]
	v_pk_mul_f32 v[18:19], v[18:19], v[26:27]
	v_pk_mul_f32 v[16:17], v[16:17], v[28:29]
	v_pk_mul_f32 v[18:19], v[18:19], v[32:33]
	v_cvt_pk_bf16_f32 v16, v16, v17
	v_cvt_pk_bf16_f32 v17, v18, v19
	global_store_dwordx2 v[24:25], v[16:17], off offset:1120
	v_max_f32_e32 v16, v90, v90
	v_max_f32_e32 v17, v69, v69
	v_max_f32_e32 v38, v17, v16
	v_sub_f32_e32 v16, v69, v38
	v_sub_f32_e32 v17, v90, v38
	v_max_f32_e32 v22, v104, v104
	v_exp_f32_e32 v16, v16
	v_exp_f32_e32 v17, v17
	v_max_f32_e32 v23, v102, v102
	v_max_f32_e32 v22, v38, v22
	v_max_f32_e32 v23, v22, v23
	v_mov_b32_e32 v90, v115
	v_sub_f32_e32 v38, v38, v22
	v_sub_f32_e32 v44, v104, v22
	v_sub_f32_e32 v22, v22, v23
	v_sub_f32_e32 v45, v102, v23
	v_exp_f32_e32 v99, v22
	v_lshl_add_u64 v[22:23], s[16:17], 0, v[20:21]
	v_pk_mul_f32 v[20:21], v[90:91], v[16:17]
	v_exp_f32_e32 v95, v38
	v_pk_fma_f32 v[40:41], v[90:91], v[16:17], v[20:21] op_sel_hi:[1,1,0]
	v_lshlrev_b32_e32 v18, 16, v100
	v_exp_f32_e32 v40, v44
	v_and_b32_e32 v19, 0xffff0000, v100
	v_lshlrev_b32_e32 v24, 16, v101
	v_and_b32_e32 v25, 0xffff0000, v101
	v_lshl_add_u64 v[38:39], v[22:23], 0, s[12:13]
	v_pk_mul_f32 v[42:43], v[20:21], v[18:19] op_sel:[1,0]
	v_pk_mul_f32 v[24:25], v[20:21], v[24:25] op_sel:[1,0]
	v_mov_b32_e32 v22, v95
	v_lshl_add_u64 v[18:19], v[38:39], 0, v[74:75]
	v_pk_fma_f32 v[38:39], v[12:13], v[16:17], v[42:43] op_sel_hi:[1,0,1]
	v_pk_fma_f32 v[14:15], v[14:15], v[16:17], v[24:25] op_sel_hi:[1,0,1]
	v_pk_mul_f32 v[24:25], v[22:23], v[38:39] op_sel_hi:[0,1]
	v_pk_mul_f32 v[38:39], v[22:23], v[14:15] op_sel_hi:[0,1]
	v_pk_mul_f32 v[14:15], v[94:95], v[40:41]
	v_lshlrev_b32_e32 v26, 16, v106
	v_pk_fma_f32 v[40:41], v[94:95], v[40:41], v[14:15] op_sel_hi:[1,1,0]
	v_and_b32_e32 v27, 0xffff0000, v106
	v_exp_f32_e32 v40, v45
	v_lshlrev_b32_e32 v32, 16, v107
	v_and_b32_e32 v33, 0xffff0000, v107
	v_mov_b32_e32 v12, v99
	v_pk_fma_f32 v[24:25], v[14:15], v[26:27], v[24:25] op_sel_hi:[0,1,1]
	v_pk_fma_f32 v[32:33], v[14:15], v[32:33], v[38:39] op_sel_hi:[0,1,1]
	v_pk_mul_f32 v[38:39], v[12:13], v[24:25] op_sel_hi:[0,1]
	v_pk_mul_f32 v[24:25], v[98:99], v[40:41]
	v_lshlrev_b32_e32 v36, 16, v109
	v_add_f32_e32 v13, v24, v25
	v_rcp_f32_e32 v26, v13
	v_and_b32_e32 v37, 0xffff0000, v109
	v_pk_mul_f32 v[32:33], v[12:13], v[32:33] op_sel_hi:[0,1]
	v_pk_fma_f32 v[34:35], v[24:25], v[34:35], v[38:39] op_sel_hi:[0,1,1]
	v_pk_fma_f32 v[32:33], v[24:25], v[36:37], v[32:33] op_sel_hi:[0,1,1]
	v_pk_mul_f32 v[34:35], v[26:27], v[34:35] op_sel_hi:[0,1]
	v_pk_mul_f32 v[32:33], v[26:27], v[32:33] op_sel_hi:[0,1]
	v_lshlrev_b32_e32 v42, 16, v97
	v_and_b32_e32 v43, 0xffff0000, v97
	s_waitcnt vmcnt(7)
	v_mov_b32_e32 v28, v242
	v_mov_b32_e32 v29, v243
	v_lshlrev_b32_e32 v36, 16, v28
	v_and_b32_e32 v37, 0xffff0000, v28
	v_lshlrev_b32_e32 v28, 16, v29
	v_and_b32_e32 v29, 0xffff0000, v29
	v_mul_f32_e32 v13, 0xbfb8aa3b, v36
	v_mul_f32_e32 v17, 0xbfb8aa3b, v37
	v_mul_f32_e32 v23, 0xbfb8aa3b, v28
	v_mul_f32_e32 v27, 0xbfb8aa3b, v29
	v_exp_f32_e32 v13, v13
	v_exp_f32_e32 v17, v17
	v_exp_f32_e32 v23, v23
	v_exp_f32_e32 v27, v27
	v_add_f32_e32 v13, 1.0, v13
	v_add_f32_e32 v17, 1.0, v17
	v_add_f32_e32 v23, 1.0, v23
	v_add_f32_e32 v27, 1.0, v27
	v_rcp_f32_e32 v38, v13
	v_rcp_f32_e32 v39, v17
	v_rcp_f32_e32 v40, v23
	v_rcp_f32_e32 v41, v27
	v_pk_mul_f32 v[34:35], v[34:35], v[36:37]
	v_pk_mul_f32 v[28:29], v[32:33], v[28:29]
	v_pk_mul_f32 v[32:33], v[34:35], v[38:39]
	v_pk_mul_f32 v[28:29], v[28:29], v[40:41]
	v_cvt_pk_bf16_f32 v32, v32, v33
	v_cvt_pk_bf16_f32 v33, v28, v29
	global_store_dwordx2 v[18:19], v[32:33], off offset:1024
	v_lshlrev_b32_e32 v32, 16, v88
	v_and_b32_e32 v33, 0xffff0000, v88
	v_lshlrev_b32_e32 v34, 16, v89
	v_and_b32_e32 v35, 0xffff0000, v89
	v_pk_mul_f32 v[32:33], v[20:21], v[32:33] op_sel:[1,0]
	v_pk_mul_f32 v[34:35], v[20:21], v[34:35] op_sel:[1,0]
	v_pk_fma_f32 v[8:9], v[8:9], v[16:17], v[32:33] op_sel_hi:[1,0,1]
	v_pk_fma_f32 v[10:11], v[10:11], v[16:17], v[34:35] op_sel_hi:[1,0,1]
	v_lshlrev_b32_e32 v36, 16, v92
	v_and_b32_e32 v37, 0xffff0000, v92
	v_lshlrev_b32_e32 v38, 16, v93
	v_and_b32_e32 v39, 0xffff0000, v93
	v_pk_mul_f32 v[8:9], v[22:23], v[8:9] op_sel_hi:[0,1]
	v_pk_mul_f32 v[10:11], v[22:23], v[10:11] op_sel_hi:[0,1]
	v_pk_fma_f32 v[8:9], v[14:15], v[36:37], v[8:9] op_sel_hi:[0,1,1]
	v_pk_fma_f32 v[10:11], v[14:15], v[38:39], v[10:11] op_sel_hi:[0,1,1]
	v_lshlrev_b32_e32 v40, 16, v96
	v_and_b32_e32 v41, 0xffff0000, v96
	v_pk_mul_f32 v[8:9], v[12:13], v[8:9] op_sel_hi:[0,1]
	v_pk_mul_f32 v[10:11], v[12:13], v[10:11] op_sel_hi:[0,1]
	v_pk_fma_f32 v[8:9], v[24:25], v[40:41], v[8:9] op_sel_hi:[0,1,1]
	v_pk_fma_f32 v[10:11], v[24:25], v[42:43], v[10:11] op_sel_hi:[0,1,1]
	v_pk_mul_f32 v[8:9], v[26:27], v[8:9] op_sel_hi:[0,1]
	v_pk_mul_f32 v[10:11], v[26:27], v[10:11] op_sel_hi:[0,1]
	v_lshlrev_b32_e32 v38, 16, v87
	v_and_b32_e32 v39, 0xffff0000, v87
	s_waitcnt vmcnt(7)
	v_mov_b32_e32 v28, v244
	v_mov_b32_e32 v29, v245
	v_lshlrev_b32_e32 v32, 16, v28
	v_and_b32_e32 v33, 0xffff0000, v28
	v_lshlrev_b32_e32 v28, 16, v29
	v_and_b32_e32 v29, 0xffff0000, v29
	v_mul_f32_e32 v13, 0xbfb8aa3b, v32
	v_mul_f32_e32 v17, 0xbfb8aa3b, v33
	v_mul_f32_e32 v23, 0xbfb8aa3b, v28
	v_mul_f32_e32 v27, 0xbfb8aa3b, v29
	v_exp_f32_e32 v13, v13
	v_exp_f32_e32 v17, v17
	v_exp_f32_e32 v23, v23
	v_exp_f32_e32 v27, v27
	v_add_f32_e32 v13, 1.0, v13
	v_add_f32_e32 v17, 1.0, v17
	v_add_f32_e32 v23, 1.0, v23
	v_add_f32_e32 v27, 1.0, v27
	v_rcp_f32_e32 v34, v13
	v_rcp_f32_e32 v35, v17
	v_rcp_f32_e32 v36, v23
	v_rcp_f32_e32 v37, v27
	v_pk_mul_f32 v[8:9], v[8:9], v[32:33]
	v_pk_mul_f32 v[10:11], v[10:11], v[28:29]
	v_pk_mul_f32 v[8:9], v[8:9], v[34:35]
	v_pk_mul_f32 v[10:11], v[10:11], v[36:37]
	v_cvt_pk_bf16_f32 v8, v8, v9
	v_cvt_pk_bf16_f32 v9, v10, v11
	global_store_dwordx2 v[18:19], v[8:9], off offset:1056
	v_lshlrev_b32_e32 v10, 16, v82
	v_and_b32_e32 v11, 0xffff0000, v82
	v_lshlrev_b32_e32 v28, 16, v83
	v_and_b32_e32 v29, 0xffff0000, v83
	v_pk_mul_f32 v[10:11], v[20:21], v[10:11] op_sel:[1,0]
	v_pk_mul_f32 v[28:29], v[20:21], v[28:29] op_sel:[1,0]
	v_pk_fma_f32 v[4:5], v[4:5], v[16:17], v[10:11] op_sel_hi:[1,0,1]
	v_pk_fma_f32 v[6:7], v[6:7], v[16:17], v[28:29] op_sel_hi:[1,0,1]
	v_lshlrev_b32_e32 v32, 16, v84
	v_and_b32_e32 v33, 0xffff0000, v84
	v_lshlrev_b32_e32 v34, 16, v85
	v_and_b32_e32 v35, 0xffff0000, v85
	v_pk_mul_f32 v[4:5], v[22:23], v[4:5] op_sel_hi:[0,1]
	v_pk_mul_f32 v[6:7], v[22:23], v[6:7] op_sel_hi:[0,1]
	v_pk_fma_f32 v[4:5], v[14:15], v[32:33], v[4:5] op_sel_hi:[0,1,1]
	v_pk_fma_f32 v[6:7], v[14:15], v[34:35], v[6:7] op_sel_hi:[0,1,1]
	v_lshlrev_b32_e32 v36, 16, v86
	v_and_b32_e32 v37, 0xffff0000, v86
	v_pk_mul_f32 v[4:5], v[12:13], v[4:5] op_sel_hi:[0,1]
	v_pk_mul_f32 v[6:7], v[12:13], v[6:7] op_sel_hi:[0,1]
	v_pk_fma_f32 v[4:5], v[24:25], v[36:37], v[4:5] op_sel_hi:[0,1,1]
	v_pk_fma_f32 v[6:7], v[24:25], v[38:39], v[6:7] op_sel_hi:[0,1,1]
	v_pk_mul_f32 v[4:5], v[26:27], v[4:5] op_sel_hi:[0,1]
	v_pk_mul_f32 v[6:7], v[26:27], v[6:7] op_sel_hi:[0,1]
	s_waitcnt vmcnt(7)
	v_mov_b32_e32 v8, v246
	v_mov_b32_e32 v9, v247
	v_lshlrev_b32_e32 v10, 16, v8
	v_and_b32_e32 v11, 0xffff0000, v8
	v_lshlrev_b32_e32 v8, 16, v9
	v_and_b32_e32 v9, 0xffff0000, v9
	v_mul_f32_e32 v13, 0xbfb8aa3b, v10
	v_mul_f32_e32 v17, 0xbfb8aa3b, v11
	v_mul_f32_e32 v23, 0xbfb8aa3b, v8
	v_mul_f32_e32 v27, 0xbfb8aa3b, v9
	v_exp_f32_e32 v13, v13
	v_exp_f32_e32 v17, v17
	v_exp_f32_e32 v23, v23
	v_exp_f32_e32 v27, v27
	v_add_f32_e32 v13, 1.0, v13
	v_add_f32_e32 v17, 1.0, v17
	v_add_f32_e32 v23, 1.0, v23
	v_add_f32_e32 v27, 1.0, v27
	v_rcp_f32_e32 v28, v13
	v_rcp_f32_e32 v29, v17
	v_rcp_f32_e32 v32, v23
	v_rcp_f32_e32 v33, v27
	v_pk_mul_f32 v[4:5], v[4:5], v[10:11]
	v_pk_mul_f32 v[6:7], v[6:7], v[8:9]
	v_pk_mul_f32 v[4:5], v[4:5], v[28:29]
	v_pk_mul_f32 v[6:7], v[6:7], v[32:33]
	v_cvt_pk_bf16_f32 v4, v4, v5
	v_cvt_pk_bf16_f32 v5, v6, v7
	global_store_dwordx2 v[18:19], v[4:5], off offset:1088
	v_lshlrev_b32_e32 v6, 16, v76
	v_and_b32_e32 v7, 0xffff0000, v76
	v_pk_mul_f32 v[6:7], v[20:21], v[6:7] op_sel:[1,0]
	v_lshlrev_b32_e32 v8, 16, v77
	v_and_b32_e32 v9, 0xffff0000, v77
	v_pk_fma_f32 v[0:1], v[0:1], v[16:17], v[6:7] op_sel_hi:[1,0,1]
	v_lshlrev_b32_e32 v10, 16, v80
	v_and_b32_e32 v11, 0xffff0000, v80
	v_pk_mul_f32 v[8:9], v[20:21], v[8:9] op_sel:[1,0]
	v_pk_mul_f32 v[0:1], v[22:23], v[0:1] op_sel_hi:[0,1]
	v_pk_fma_f32 v[2:3], v[2:3], v[16:17], v[8:9] op_sel_hi:[1,0,1]
	v_pk_fma_f32 v[0:1], v[14:15], v[10:11], v[0:1] op_sel_hi:[0,1,1]
	v_lshlrev_b32_e32 v28, 16, v81
	v_and_b32_e32 v29, 0xffff0000, v81
	v_pk_mul_f32 v[2:3], v[22:23], v[2:3] op_sel_hi:[0,1]
	v_pk_fma_f32 v[2:3], v[14:15], v[28:29], v[2:3] op_sel_hi:[0,1,1]
	v_lshlrev_b32_e32 v30, 16, v78
	v_and_b32_e32 v31, 0xffff0000, v78
	v_lshlrev_b32_e32 v32, 16, v79
	v_and_b32_e32 v33, 0xffff0000, v79
	v_pk_mul_f32 v[0:1], v[12:13], v[0:1] op_sel_hi:[0,1]
	v_pk_mul_f32 v[2:3], v[12:13], v[2:3] op_sel_hi:[0,1]
	v_pk_fma_f32 v[0:1], v[24:25], v[30:31], v[0:1] op_sel_hi:[0,1,1]
	v_pk_fma_f32 v[2:3], v[24:25], v[32:33], v[2:3] op_sel_hi:[0,1,1]
	v_pk_mul_f32 v[0:1], v[26:27], v[0:1] op_sel_hi:[0,1]
	v_pk_mul_f32 v[2:3], v[26:27], v[2:3] op_sel_hi:[0,1]
	s_waitcnt vmcnt(7)
	v_mov_b32_e32 v4, v248
	v_mov_b32_e32 v5, v249
	v_lshlrev_b32_e32 v6, 16, v4
	v_and_b32_e32 v7, 0xffff0000, v4
	v_lshlrev_b32_e32 v4, 16, v5
	v_and_b32_e32 v5, 0xffff0000, v5
	v_mul_f32_e32 v8, 0xbfb8aa3b, v6
	v_mul_f32_e32 v9, 0xbfb8aa3b, v7
	v_mul_f32_e32 v10, 0xbfb8aa3b, v4
	v_mul_f32_e32 v11, 0xbfb8aa3b, v5
	v_exp_f32_e32 v8, v8
	v_exp_f32_e32 v9, v9
	v_exp_f32_e32 v10, v10
	v_exp_f32_e32 v11, v11
	v_add_f32_e32 v8, 1.0, v8
	v_add_f32_e32 v9, 1.0, v9
	v_add_f32_e32 v10, 1.0, v10
	v_add_f32_e32 v11, 1.0, v11
	v_rcp_f32_e32 v8, v8
	v_rcp_f32_e32 v9, v9
	v_rcp_f32_e32 v10, v10
	v_rcp_f32_e32 v11, v11
	v_pk_mul_f32 v[0:1], v[0:1], v[6:7]
	v_pk_mul_f32 v[2:3], v[2:3], v[4:5]
	v_pk_mul_f32 v[0:1], v[0:1], v[8:9]
	v_pk_mul_f32 v[2:3], v[2:3], v[10:11]
	v_cvt_pk_bf16_f32 v0, v0, v1
	v_cvt_pk_bf16_f32 v1, v2, v3
	global_store_dwordx2 v[18:19], v[0:1], off offset:1120
	s_cbranch_scc0 .LBB0_298
.LBB0_278:
	s_ashr_i32 s14, s23, 4
	s_and_b32 s12, s23, 15
	s_min_u32 s74, s12, 3
	s_ashr_i32 s15, s14, 31
	s_lshl_b64 s[0:1], s[14:15], 12
	s_lshl_b32 s24, s12, 8
	s_or_b32 s16, s0, s24
	s_mov_b32 s17, s1
	s_lshl_b64 s[16:17], s[16:17], 7
	s_add_u32 s18, s66, s16
	s_addc_u32 s19, s67, s17
	s_lshl_b64 s[20:21], s[14:15], 19
	s_add_u32 s15, s68, s20
	s_addc_u32 s21, s69, s21
	s_lshl_b32 s20, s12, 9
	s_add_u32 s20, s15, s20
	s_addc_u32 s21, s21, 0
	v_mov_b32_e32 v65, v121
	v_mov_b32_e32 v69, v121
	v_lshl_add_u64 v[0:1], s[18:19], 0, v[56:57]
	v_lshl_add_u64 v[2:3], s[18:19], 0, v[60:61]
	v_lshl_add_u64 v[8:9], s[18:19], 0, v[62:63]
	v_lshl_add_u64 v[10:11], s[18:19], 0, v[120:121]
	v_lshl_add_u64 v[16:17], s[20:21], 0, v[64:65]
	v_mov_b32_e32 v67, v121
	v_lshl_add_u64 v[18:19], s[20:21], 0, v[68:69]
	v_lshl_add_u64 v[0:1], v[0:1], 0, v[58:59]
	v_lshl_add_u64 v[4:5], v[2:3], 0, v[58:59]
	v_lshl_add_u64 v[8:9], v[8:9], 0, v[58:59]
	v_lshl_add_u64 v[12:13], v[10:11], 0, v[58:59]
	v_lshl_add_u64 v[16:17], v[16:17], 0, v[66:67]
	v_lshl_add_u64 v[20:21], v[18:19], 0, v[66:67]
	v_mov_b32_e32 v71, v121
	v_mov_b32_e32 v73, v121
	global_load_dwordx4 v[0:3], v[0:1], off
	s_nop 0
	global_load_dwordx4 v[4:7], v[4:5], off
	s_nop 0
	global_load_dwordx4 v[8:11], v[8:9], off
	s_nop 0
	global_load_dwordx4 v[12:15], v[12:13], off
	s_nop 0
	global_load_dwordx4 v[16:19], v[16:17], off
	s_nop 0
	global_load_dwordx4 v[36:39], v[20:21], off
	v_lshl_add_u64 v[20:21], s[20:21], 0, v[70:71]
	v_lshl_add_u64 v[22:23], s[20:21], 0, v[72:73]
	v_lshl_add_u64 v[20:21], v[20:21], 0, v[66:67]
	v_lshl_add_u64 v[22:23], v[22:23], 0, v[66:67]
	v_lshl_add_u64 v[32:33], v[50:51], 0, s[16:17]
	global_load_dwordx4 v[40:43], v[20:21], off
	global_load_dwordx4 v[44:47], v[22:23], off
	s_nop 0
	global_load_dwordx4 v[20:23], v[32:33], off
	global_load_dwordx4 v[24:27], v[32:33], off offset:64
	global_load_dwordx4 v[28:31], v[32:33], off offset:2048
	s_nop 0
	global_load_dwordx4 v[32:35], v[32:33], off offset:2112
	v_add_u32_e32 v140, s24, v48
	v_mov_b32_e32 v141, v121
	s_cmp_lg_u32 s12, 0
	v_lshl_add_u64 v[76:77], s[0:1], 0, v[140:141]
	v_mov_b64_e32 v[110:111], 0
	s_cselect_b64 s[18:19], -1, 0
	s_cmp_eq_u32 s12, 0
	v_mov_b64_e32 v[112:113], 0
	v_mov_b64_e32 v[118:119], 0
	v_mov_b64_e32 v[128:129], 0
	v_mov_b64_e32 v[142:143], 0
	v_mov_b32_e32 v132, 0xf149f2ca
	v_mov_b32_e32 v133, 0
	s_cbranch_scc1 .LBB0_280
	v_mad_u64_u32 v[78:79], s[16:17], v76, 24, s[42:43]
	v_mad_i32_i24 v79, v77, 24, v79
	global_load_dwordx2 v[132:133], v[78:79], off
	v_mad_u64_u32 v[78:79], s[16:17], v76, s4, v[52:53]
	v_mad_i32_i24 v79, v77, s4, v79
	global_load_dwordx2 v[142:143], v[78:79], off
	global_load_dwordx2 v[128:129], v[78:79], off offset:32
	global_load_dwordx2 v[118:119], v[78:79], off offset:64
	global_load_dwordx2 v[112:113], v[78:79], off offset:96
.LBB0_280:
	v_mad_u64_u32 v[78:79], s[16:17], v76, 3, 0
	s_cmp_gt_u32 s12, 1
	v_mad_i32_i24 v79, v77, 3, v79
	v_mov_b32_e32 v136, 0
	s_cselect_b64 s[16:17], -1, 0
	s_cmp_lt_u32 s12, 2
	v_mov_b64_e32 v[124:125], 0
	v_mov_b64_e32 v[130:131], 0
	v_mov_b64_e32 v[150:151], 0
	v_mov_b32_e32 v148, 0xf149f2ca
	v_mov_b32_e32 v138, 0
	s_cbranch_scc1 .LBB0_282
	v_lshl_add_u64 v[76:77], v[78:79], 0, 1
	v_lshl_add_u64 v[80:81], v[76:77], 3, s[42:43]
	v_lshlrev_b64 v[76:77], 7, v[76:77]
	v_lshl_add_u64 v[76:77], v[52:53], 0, v[76:77]
	global_load_dword v148, v[80:81], off
	global_load_dword v138, v[80:81], off offset:4
	global_load_dwordx2 v[150:151], v[76:77], off
	global_load_dwordx2 v[130:131], v[76:77], off offset:32
	global_load_dwordx2 v[124:125], v[76:77], off offset:64
	global_load_dwordx2 v[110:111], v[76:77], off offset:96
.LBB0_282:
	s_cmp_gt_u32 s12, 2
	v_mov_b32_e32 v90, 0xf149f2ca
	v_mov_b64_e32 v[76:77], 0
	s_cselect_b64 s[20:21], -1, 0
	s_cmp_lt_u32 s12, 3
	v_mov_b64_e32 v[116:117], 0
	v_mov_b64_e32 v[126:127], 0
	v_mov_b64_e32 v[134:135], 0
	v_mov_b64_e32 v[154:155], 0
	v_mov_b32_e32 v152, 0xf149f2ca
	s_cbranch_scc1 .LBB0_284
	v_lshl_add_u64 v[78:79], v[78:79], 0, 2
	v_lshl_add_u64 v[80:81], v[78:79], 3, s[42:43]
	v_lshlrev_b64 v[78:79], 7, v[78:79]
	v_lshl_add_u64 v[78:79], v[52:53], 0, v[78:79]
	global_load_dword v152, v[80:81], off
	global_load_dword v136, v[80:81], off offset:4
	global_load_dwordx2 v[154:155], v[78:79], off
	global_load_dwordx2 v[134:135], v[78:79], off offset:32
	global_load_dwordx2 v[126:127], v[78:79], off offset:64
	global_load_dwordx2 v[116:117], v[78:79], off offset:96

.LBB0_286:
	v_mad_u64_u32 v[114:115], s[0:1], v78, 3, 0
	v_mad_i32_i24 v115, v79, 3, v115
	v_mov_b32_e32 v102, 0xf149f2ca
	v_mov_b64_e32 v[78:79], 0
	s_andn2_b64 vcc, exec, s[16:17]
	v_mov_b64_e32 v[80:81], 0
	v_mov_b64_e32 v[84:85], 0
	v_mov_b64_e32 v[92:93], 0
	v_mov_b64_e32 v[106:107], 0
	v_mov_b32_e32 v104, 0xf149f2ca
	s_cbranch_vccnz .LBB0_288
	v_lshl_add_u64 v[80:81], v[114:115], 0, 1
	v_lshl_add_u64 v[84:85], v[80:81], 3, s[42:43]
	v_lshlrev_b64 v[80:81], 7, v[80:81]
	v_lshl_add_u64 v[80:81], v[52:53], 0, v[80:81]
	global_load_dword v104, v[84:85], off
	global_load_dword v94, v[84:85], off offset:4
	global_load_dwordx2 v[106:107], v[80:81], off
	global_load_dwordx2 v[92:93], v[80:81], off offset:32
	s_nop 0
	global_load_dwordx2 v[84:85], v[80:81], off offset:64
	s_nop 0
	global_load_dwordx2 v[80:81], v[80:81], off offset:96
.LBB0_288:
	v_mov_b32_e32 v98, 0
	s_andn2_b64 vcc, exec, s[20:21]
	v_mov_b64_e32 v[86:87], 0
	v_mov_b64_e32 v[96:97], 0
	v_mov_b64_e32 v[108:109], 0
	s_cbranch_vccnz .LBB0_290
	v_lshl_add_u64 v[78:79], v[114:115], 0, 2
	v_lshl_add_u64 v[86:87], v[78:79], 3, s[42:43]
	v_lshlrev_b64 v[78:79], 7, v[78:79]
	v_lshl_add_u64 v[78:79], v[52:53], 0, v[78:79]
	global_load_dword v102, v[86:87], off
	global_load_dword v98, v[86:87], off offset:4
	global_load_dwordx2 v[108:109], v[78:79], off
	global_load_dwordx2 v[96:97], v[78:79], off offset:32
	s_nop 0
	global_load_dwordx2 v[86:87], v[78:79], off offset:64
	s_nop 0
	global_load_dwordx2 v[78:79], v[78:79], off offset:96
.LBB0_290:
	s_barrier
	s_cmp_lt_u32 s74, 2
	s_cbranch_scc1 .Lown_wa1
	s_cmp_eq_u32 s74, 2
	s_cbranch_scc1 .Lown_w21
	s_waitcnt vmcnt(38)
	s_branch .Lown_wd1
.Lown_w21:
	s_waitcnt vmcnt(26)
	s_branch .Lown_wd1
.Lown_wa1:
	s_cmp_eq_u32 s74, 0
	s_cbranch_scc1 .Lown_w01
	s_waitcnt vmcnt(14)
	s_branch .Lown_wd1

.Lown_wd1:
	ds_write_b128 v175, v[0:3]
	ds_write_b128 v123, v[4:7]
	ds_write_b128 v176, v[8:11]
	ds_write_b128 v177, v[12:15]
	ds_write_b128 v182, v[16:19] offset:36864
	ds_write_b128 v183, v[36:39] offset:36864
	ds_write_b128 v185, v[40:43] offset:36864
	ds_write_b128 v186, v[44:47] offset:36864
	v_mov_b32_e32 v2, v121
	v_mov_b32_e32 v3, v121
	v_mov_b32_e32 v0, v121
	v_mov_b32_e32 v1, v121
	v_mov_b64_e32 v[6:7], v[2:3]
	v_mov_b64_e32 v[10:11], v[2:3]
	v_mov_b64_e32 v[14:15], v[2:3]
	v_mov_b64_e32 v[18:19], v[2:3]
	v_mov_b64_e32 v[38:39], v[2:3]
	v_mov_b64_e32 v[42:43], v[2:3]
	v_mov_b64_e32 v[46:47], v[2:3]
	v_mov_b32_e32 v114, v121
	v_mov_b32_e32 v115, v121
	v_mov_b32_e32 v69, 0xf149f2ca
	s_mov_b32 s12, 0
	v_mov_b32_e32 v65, v197
	v_mov_b32_e32 v67, v187
	v_mov_b64_e32 v[4:5], v[0:1]
	v_mov_b64_e32 v[8:9], v[0:1]
	v_mov_b64_e32 v[12:13], v[0:1]
	v_mov_b64_e32 v[16:17], v[0:1]
	v_mov_b64_e32 v[36:37], v[0:1]
	v_mov_b64_e32 v[40:41], v[0:1]
	v_mov_b32_e32 v71, 0xf149f2ca
	v_mov_b64_e32 v[44:45], v[0:1]
	s_waitcnt lgkmcnt(0)
	s_barrier
	s_branch .LBB0_293

.LBB0_293:
	s_add_i32 s0, s12, 63
	v_cmp_le_u32_e32 vcc, s0, v174
	s_and_saveexec_b64 s[0:1], vcc
	s_xor_b64 s[0:1], exec, s[0:1]
	s_cbranch_execz .LBB0_295
	ds_read_b128 v[156:159], v67
	ds_read_b128 v[160:163], v67 offset:64
	ds_read_b128 v[168:171], v67 offset:2304
	ds_read_b128 v[200:203], v67 offset:2368
	s_cmp_lt_u32 s74, 2
	s_cbranch_scc1 .Lown_wa2
	s_cmp_eq_u32 s74, 2
	s_cbranch_scc1 .Lown_w22
	s_waitcnt vmcnt(34)
	s_branch .Lown_wd2
.Lown_w22:
	s_waitcnt vmcnt(22)
	s_branch .Lown_wd2
.Lown_wa2:
	s_cmp_eq_u32 s74, 0
	s_cbranch_scc1 .Lown_w02
	s_waitcnt vmcnt(10)
	s_branch .Lown_wd2

.Lown_wd2:
	s_waitcnt lgkmcnt(1)
	v_mfma_f32_16x16x32_bf16 v[204:207], v[168:171], v[20:23], 0
	v_mfma_f32_16x16x32_bf16 v[168:171], v[168:171], v[28:31], 0
	s_waitcnt lgkmcnt(0)
	v_mfma_f32_16x16x32_bf16 v[204:207], v[200:203], v[24:27], v[204:207]
	v_mfma_f32_16x16x32_bf16 v[168:171], v[200:203], v[32:35], v[168:171]
	ds_read_b128 v[200:203], v67 offset:4608
	ds_read_b128 v[208:211], v67 offset:4672
	ds_read_b128 v[216:219], v67 offset:6912
	ds_read_b128 v[220:223], v67 offset:6976
	v_mfma_f32_16x16x32_bf16 v[164:167], v[156:159], v[20:23], 0
	v_mfma_f32_16x16x32_bf16 v[156:159], v[156:159], v[28:31], 0
	v_mfma_f32_16x16x32_bf16 v[164:167], v[160:163], v[24:27], v[164:167]
	s_waitcnt lgkmcnt(3)
	v_mfma_f32_16x16x32_bf16 v[212:215], v[200:203], v[20:23], 0
	v_mfma_f32_16x16x32_bf16 v[200:203], v[200:203], v[28:31], 0
	s_nop 4
	v_max3_f32 v73, v164, s5, v165
	v_max3_f32 v73, v73, v166, v167
	v_max3_f32 v73, v73, v204, v205
	s_waitcnt lgkmcnt(1)
	v_mfma_f32_16x16x32_bf16 v[224:227], v[216:219], v[20:23], 0
	v_max3_f32 v73, v73, v206, v207
	v_mfma_f32_16x16x32_bf16 v[158:161], v[160:163], v[32:35], v[156:159]
	v_mfma_f32_16x16x32_bf16 v[212:215], v[208:211], v[24:27], v[212:215]
	s_waitcnt lgkmcnt(0)
	v_mfma_f32_16x16x32_bf16 v[224:227], v[220:223], v[24:27], v[224:227]
	s_nop 4
	v_max3_f32 v75, v158, s5, v159
	v_max3_f32 v73, v73, v212, v213
	v_max3_f32 v73, v73, v214, v215
	v_mfma_f32_16x16x32_bf16 v[200:203], v[208:211], v[32:35], v[200:203]
	v_max3_f32 v75, v75, v160, v161
	v_max3_f32 v73, v73, v224, v225
	v_max3_f32 v75, v75, v168, v169
	v_mfma_f32_16x16x32_bf16 v[208:211], v[216:219], v[28:31], 0
	v_max3_f32 v73, v73, v226, v227
	v_max3_f32 v75, v75, v170, v171
	s_nop 1
	v_max3_f32 v75, v75, v200, v201
	v_mfma_f32_16x16x32_bf16 v[208:211], v[220:223], v[32:35], v[208:211]
	v_mov_b32_e32 v95, v73
	v_mov_b32_e32 v99, v73
	v_max3_f32 v75, v75, v202, v203
	s_nop 0
	v_permlane16_swap_b32_e32 v95, v99
	v_cndmask_b32_e64 v95, v95, v99, s[8:9]
	s_nop 1
	v_max3_f32 v75, v75, v208, v209
	v_max3_f32 v75, v75, v210, v211
	v_max_f32_e32 v95, v95, v95
	v_max_f32_e32 v73, v73, v95
	v_mov_b32_e32 v95, v75
	v_mov_b32_e32 v99, v75
	s_nop 1
	v_permlane16_swap_b32_e32 v95, v99
	v_cndmask_b32_e64 v95, v95, v99, s[8:9]
	v_max_f32_e32 v95, v95, v95
	v_max_f32_e32 v75, v75, v95
	v_mov_b32_e32 v95, v73
	v_mov_b32_e32 v99, v73
	s_nop 1
	v_permlane32_swap_b32_e32 v95, v99
	v_cndmask_b32_e64 v95, v95, v99, s[10:11]
	v_mov_b32_e32 v99, v75
	v_mov_b32_e32 v103, v75
	s_nop 1
	v_permlane32_swap_b32_e32 v99, v103
	v_cndmask_b32_e64 v99, v99, v103, s[10:11]
	v_max3_f32 v75, v69, v75, v99
	v_max3_f32 v73, v71, v73, v95
	v_sub_f32_e32 v69, v69, v75
	v_exp_f32_e32 v157, v69
	v_sub_f32_e32 v69, v164, v73
	v_exp_f32_e32 v172, v69
	v_sub_f32_e32 v69, v158, v75
	v_exp_f32_e32 v173, v69
	v_sub_f32_e32 v69, v165, v73
	v_exp_f32_e32 v178, v69
	v_sub_f32_e32 v69, v159, v75
	v_exp_f32_e32 v179, v69
	v_sub_f32_e32 v69, v166, v73
	v_exp_f32_e32 v216, v69
	v_sub_f32_e32 v69, v160, v75
	v_exp_f32_e32 v217, v69
	v_sub_f32_e32 v69, v167, v73
	v_exp_f32_e32 v218, v69
	v_sub_f32_e32 v69, v161, v75
	v_exp_f32_e32 v219, v69
	v_sub_f32_e32 v69, v204, v73
	v_exp_f32_e32 v220, v69
	v_sub_f32_e32 v69, v168, v75
	v_exp_f32_e32 v221, v69
	v_sub_f32_e32 v69, v205, v73
	v_exp_f32_e32 v204, v69
	v_sub_f32_e32 v69, v169, v75
	v_exp_f32_e32 v205, v69
	v_sub_f32_e32 v69, v206, v73
	v_exp_f32_e32 v222, v69
	v_sub_f32_e32 v69, v170, v75
	v_exp_f32_e32 v223, v69
	v_sub_f32_e32 v69, v207, v73
	v_exp_f32_e32 v206, v69
	v_sub_f32_e32 v69, v171, v75
	v_exp_f32_e32 v207, v69
	v_sub_f32_e32 v69, v212, v73
	v_exp_f32_e32 v228, v69
	v_sub_f32_e32 v69, v200, v75
	v_exp_f32_e32 v229, v69
	v_sub_f32_e32 v69, v213, v73
	v_exp_f32_e32 v212, v69
	v_sub_f32_e32 v69, v201, v75
	v_exp_f32_e32 v213, v69
	v_sub_f32_e32 v69, v214, v73
	v_exp_f32_e32 v230, v69
	v_sub_f32_e32 v69, v202, v75
	v_pk_add_f32 v[158:159], v[172:173], 0 op_sel_hi:[1,0]
	v_exp_f32_e32 v231, v69
	v_sub_f32_e32 v69, v215, v73
	v_pk_add_f32 v[158:159], v[178:179], v[158:159]
	v_exp_f32_e32 v214, v69
	v_sub_f32_e32 v69, v203, v75
	v_pk_add_f32 v[158:159], v[216:217], v[158:159]
	v_exp_f32_e32 v215, v69
	v_sub_f32_e32 v69, v224, v73
	ds_read2_b64 v[166:169], v65 offset1:4
	v_pk_add_f32 v[158:159], v[218:219], v[158:159]
	v_exp_f32_e32 v232, v69
	v_sub_f32_e32 v69, v208, v75
	v_pk_add_f32 v[158:159], v[220:221], v[158:159]
	v_exp_f32_e32 v233, v69
	v_sub_f32_e32 v69, v225, v73
	v_sub_f32_e32 v71, v71, v73
	v_pk_add_f32 v[158:159], v[204:205], v[158:159]
	v_exp_f32_e32 v208, v69
	v_sub_f32_e32 v69, v209, v75
	v_exp_f32_e32 v156, v71
	v_pk_add_f32 v[158:159], v[222:223], v[158:159]
	v_exp_f32_e32 v209, v69
	v_sub_f32_e32 v69, v226, v73
	ds_read2_b64 v[200:203], v65 offset0:8 offset1:12
	v_pk_add_f32 v[170:171], v[206:207], v[158:159]
	v_exp_f32_e32 v224, v69
	v_sub_f32_e32 v69, v210, v75
	v_exp_f32_e32 v225, v69
	v_sub_f32_e32 v69, v227, v73
	v_pk_add_f32 v[170:171], v[228:229], v[170:171]
	v_exp_f32_e32 v210, v69
	v_sub_f32_e32 v69, v211, v75
	v_cvt_pk_bf16_f32 v158, v172, v178
	v_pk_add_f32 v[170:171], v[212:213], v[170:171]
	v_mov_b32_e32 v178, v157
	v_exp_f32_e32 v211, v69
	v_pk_mul_f32 v[46:47], v[46:47], v[156:157] op_sel_hi:[1,0]
	v_pk_mul_f32 v[44:45], v[44:45], v[156:157] op_sel_hi:[1,0]
	v_cvt_pk_bf16_f32 v159, v216, v218
	v_cvt_pk_bf16_f32 v160, v220, v204
	v_cvt_pk_bf16_f32 v161, v222, v206
	v_pk_add_f32 v[226:227], v[230:231], v[170:171]
	v_pk_mul_f32 v[14:15], v[14:15], v[178:179] op_sel_hi:[1,0]
	v_pk_mul_f32 v[12:13], v[12:13], v[178:179] op_sel_hi:[1,0]
	v_cvt_pk_bf16_f32 v170, v173, v179
	v_cvt_pk_bf16_f32 v171, v217, v219
	v_cvt_pk_bf16_f32 v172, v221, v205
	v_cvt_pk_bf16_f32 v173, v223, v207
	s_waitcnt lgkmcnt(1)
	v_mfma_f32_16x16x32_bf16 v[44:47], v[166:169], v[158:161], v[44:47]
	v_add_u32_e32 v69, 0x2000, v65
	ds_read2_b64 v[204:207], v69 offset0:32 offset1:36
	v_cvt_pk_bf16_f32 v162, v228, v212
	v_mfma_f32_16x16x32_bf16 v[12:15], v[166:169], v[170:173], v[12:15]
	v_cvt_pk_bf16_f32 v163, v230, v214
	v_cvt_pk_bf16_f32 v164, v232, v208
	v_cvt_pk_bf16_f32 v165, v224, v210
	v_cvt_pk_bf16_f32 v166, v229, v213
	v_cvt_pk_bf16_f32 v167, v231, v215
	v_cvt_pk_bf16_f32 v168, v233, v209
	v_cvt_pk_bf16_f32 v169, v225, v211
	s_waitcnt lgkmcnt(1)
	v_mfma_f32_16x16x32_bf16 v[44:47], v[200:203], v[162:165], v[44:47]
	v_mul_f32_e64 v42, v42, v156
	v_mul_f32_e64 v43, v43, v156
	v_pk_mul_f32 v[40:41], v[40:41], v[156:157] op_sel_hi:[1,0]
	v_pk_mul_f32 v[10:11], v[10:11], v[178:179] op_sel_hi:[1,0]
	v_mfma_f32_16x16x32_bf16 v[12:15], v[200:203], v[166:169], v[12:15]
	v_add_f32_e64 v200, v214, v226
	v_add_f32_e64 v201, v215, v227
	v_pk_mul_f32 v[8:9], v[8:9], v[178:179] op_sel_hi:[1,0]
	v_pk_add_f32 v[212:213], v[232:233], v[200:201]
	ds_read2_b64 v[200:203], v69 offset0:40 offset1:44
	v_add_u32_e32 v69, 0x4000, v65
	s_waitcnt lgkmcnt(1)
	v_mfma_f32_16x16x32_bf16 v[40:43], v[204:207], v[158:161], v[40:43]
	v_add_f32_e64 v208, v208, v212
	v_add_f32_e64 v209, v209, v213
	v_pk_mul_f32 v[38:39], v[38:39], v[156:157] op_sel_hi:[1,0]
	v_pk_add_f32 v[208:209], v[224:225], v[208:209]
	v_mfma_f32_16x16x32_bf16 v[8:11], v[204:207], v[170:173], v[8:11]
	ds_read2_b64 v[204:207], v69 offset0:64 offset1:68
	v_pk_add_f32 v[208:209], v[210:211], v[208:209]
	v_pk_mul_f32 v[36:37], v[36:37], v[156:157] op_sel_hi:[1,0]
	s_waitcnt lgkmcnt(1)
	v_mfma_f32_16x16x32_bf16 v[40:43], v[200:203], v[162:165], v[40:43]
	v_mov_b32_e32 v99, v209
	v_pk_mul_f32 v[6:7], v[6:7], v[178:179] op_sel_hi:[1,0]
	v_pk_mul_f32 v[4:5], v[4:5], v[178:179] op_sel_hi:[1,0]
	v_mfma_f32_16x16x32_bf16 v[8:11], v[200:203], v[166:169], v[8:11]
	ds_read2_b64 v[200:203], v69 offset0:72 offset1:76
	v_mov_b32_e32 v69, v209
	s_nop 1
	v_permlane16_swap_b32_e32 v99, v69
	v_cndmask_b32_e64 v211, v99, v69, s[8:9]
	v_add_u32_e32 v69, 0x6000, v65
	s_waitcnt lgkmcnt(1)
	v_mfma_f32_16x16x32_bf16 v[36:39], v[204:207], v[158:161], v[36:39]
	v_mul_f32_e64 v18, v18, v156
	v_mul_f32_e64 v19, v19, v156
	v_pk_mul_f32 v[16:17], v[16:17], v[156:157] op_sel_hi:[1,0]
	v_mov_b32_e32 v71, v208
	v_mfma_f32_16x16x32_bf16 v[4:7], v[204:207], v[170:173], v[4:7]
	ds_read2_b64 v[204:207], v69 offset0:96 offset1:100
	v_mov_b32_e32 v95, v208
	v_pk_mul_f32 v[2:3], v[2:3], v[178:179] op_sel_hi:[1,0]
	s_waitcnt lgkmcnt(1)
	v_mfma_f32_16x16x32_bf16 v[36:39], v[200:203], v[162:165], v[36:39]
	v_mul_f32_e64 v0, v0, v178
	v_mul_f32_e64 v1, v1, v178
	v_permlane16_swap_b32_e32 v71, v95
	v_mfma_f32_16x16x32_bf16 v[4:7], v[200:203], v[166:169], v[4:7]
	ds_read2_b64 v[200:203], v69 offset0:104 offset1:108
	v_cndmask_b32_e64 v210, v71, v95, s[8:9]
	v_pk_add_f32 v[208:209], v[208:209], v[210:211]
	s_waitcnt lgkmcnt(1)
	v_mfma_f32_16x16x32_bf16 v[16:19], v[204:207], v[158:161], v[16:19]
	v_mov_b32_e32 v71, v208
	v_mov_b32_e32 v95, v208
	v_mov_b32_e32 v99, v209
	v_mfma_f32_16x16x32_bf16 v[0:3], v[204:207], v[170:173], v[0:3]
	v_mov_b32_e32 v69, v209
	v_permlane32_swap_b32_e32 v71, v95
	s_nop 0
	v_permlane32_swap_b32_e32 v99, v69
	s_waitcnt lgkmcnt(0)
	v_mfma_f32_16x16x32_bf16 v[16:19], v[200:203], v[162:165], v[16:19]
	v_cndmask_b32_e64 v159, v99, v69, s[10:11]
	v_cndmask_b32_e64 v158, v71, v95, s[10:11]
	v_pk_add_f32 v[158:159], v[208:209], v[158:159]
	v_mfma_f32_16x16x32_bf16 v[0:3], v[200:203], v[166:169], v[0:3]
	v_fma_f32 v114, v114, v156, v158
	v_fma_f32 v115, v115, v157, v159
	v_mov_b32_e32 v71, v73
	v_mov_b32_e32 v69, v75
.LBB0_295:
	s_andn2_saveexec_b64 s[16:17], s[0:1]
	s_cbranch_execz .LBB0_292
	v_cmp_le_u32_e32 vcc, s12, v184
	s_and_saveexec_b64 s[18:19], vcc
	s_cbranch_execz .LBB0_291
	ds_read_b128 v[156:159], v67
	ds_read_b128 v[160:163], v67 offset:64
	ds_read_b128 v[168:171], v67 offset:2304
	ds_read_b128 v[200:203], v67 offset:2368
	ds_read_b128 v[204:207], v67 offset:4608
	ds_read_b128 v[208:211], v67 offset:4672
	v_add_u32_e32 v73, s12, v122
	s_cmp_lt_u32 s74, 2
	s_cbranch_scc1 .Lown_wa3
	s_cmp_eq_u32 s74, 2
	s_cbranch_scc1 .Lown_w23
	s_waitcnt vmcnt(34)
	s_branch .Lown_wd3

.Lown_wd3:
	s_waitcnt lgkmcnt(5)
	v_mfma_f32_16x16x32_bf16 v[164:167], v[156:159], v[20:23], 0
	v_cmp_le_u32_e32 vcc, v73, v49
	v_cmp_lt_u32_e64 s[0:1], v73, v49
	v_add_u32_e32 v75, 16, v73
	v_mfma_f32_16x16x32_bf16 v[156:159], v[156:159], v[28:31], 0
	v_add_u32_e32 v139, 2, v73
	v_add_u32_e32 v149, 3, v73
	s_waitcnt lgkmcnt(3)
	v_mfma_f32_16x16x32_bf16 v[216:219], v[168:171], v[20:23], 0
	v_mfma_f32_16x16x32_bf16 v[168:171], v[168:171], v[28:31], 0
	v_mfma_f32_16x16x32_bf16 v[156:159], v[160:163], v[32:35], v[156:159]
	v_mfma_f32_16x16x32_bf16 v[164:167], v[160:163], v[24:27], v[164:167]
	ds_read_b128 v[160:163], v67 offset:6912
	ds_read_b128 v[212:215], v67 offset:6976
	s_nop 4
	v_cndmask_b32_e32 v95, v198, v156, vcc
	v_cmp_gt_u32_e32 vcc, v73, v55
	s_waitcnt lgkmcnt(4)
	v_mfma_f32_16x16x32_bf16 v[168:171], v[200:203], v[32:35], v[168:171]
	v_cndmask_b32_e64 v103, v198, v157, s[0:1]
	v_cmp_lt_u32_e64 s[0:1], v73, v48
	v_cndmask_b32_e32 v99, v164, v198, vcc
	v_mfma_f32_16x16x32_bf16 v[216:219], v[200:203], v[24:27], v[216:219]
	v_cndmask_b32_e64 v105, v198, v165, s[0:1]
	v_cmp_le_u32_e64 s[0:1], v139, v49
	s_nop 1
	v_cndmask_b32_e32 v172, v168, v198, vcc
	s_waitcnt lgkmcnt(3)
	v_mfma_f32_16x16x32_bf16 v[200:203], v[204:207], v[20:23], 0
	v_cmp_le_u32_e32 vcc, v75, v54
	v_add_u32_e32 v168, 17, v73
	v_cndmask_b32_e64 v141, v198, v158, s[0:1]
	v_cmp_le_u32_e64 s[0:1], v139, v48
	v_cndmask_b32_e32 v75, v198, v216, vcc
	v_cmp_le_u32_e32 vcc, v168, v49
	v_cndmask_b32_e64 v139, v198, v166, s[0:1]
	v_cmp_le_u32_e64 s[0:1], v149, v49
	v_cndmask_b32_e32 v173, v198, v169, vcc
	v_cmp_le_u32_e32 vcc, v168, v48
	v_add_u32_e32 v168, 18, v73
	v_cndmask_b32_e64 v153, v198, v159, s[0:1]
	v_cmp_le_u32_e64 s[0:1], v149, v48
	v_cndmask_b32_e32 v178, v198, v217, vcc
	v_cmp_le_u32_e32 vcc, v168, v49
	v_cndmask_b32_e64 v149, v198, v167, s[0:1]
	s_waitcnt lgkmcnt(2)
	v_mfma_f32_16x16x32_bf16 v[164:167], v[208:211], v[24:27], v[200:203]
	v_cndmask_b32_e32 v179, v198, v170, vcc
	v_cmp_le_u32_e32 vcc, v168, v48
	v_add_u32_e32 v168, 19, v73
	v_mfma_f32_16x16x32_bf16 v[156:159], v[204:207], v[28:31], 0
	v_cndmask_b32_e32 v199, v198, v218, vcc
	v_cmp_le_u32_e32 vcc, v168, v49
	v_add_u32_e32 v169, 48, v73
	v_mfma_f32_16x16x32_bf16 v[156:159], v[208:211], v[32:35], v[156:159]
	v_cndmask_b32_e32 v204, v198, v171, vcc
	v_cmp_le_u32_e32 vcc, v168, v48
	v_add_u32_e32 v168, 32, v73
	s_waitcnt lgkmcnt(1)
	v_mfma_f32_16x16x32_bf16 v[200:203], v[160:163], v[20:23], 0
	v_cndmask_b32_e32 v205, v198, v219, vcc
	v_cmp_le_u32_e32 vcc, v168, v48
	v_max3_f32 v209, v95, s5, v103
	v_mfma_f32_16x16x32_bf16 v[160:163], v[160:163], v[28:31], 0
	v_cndmask_b32_e32 v206, v198, v164, vcc
	v_add_u32_e32 v164, 33, v73
	v_cmp_le_u32_e32 vcc, v164, v48
	v_max3_f32 v209, v209, v141, v153
	v_max3_f32 v209, v209, v172, v173
	v_cndmask_b32_e32 v207, v198, v165, vcc
	v_add_u32_e32 v165, 34, v73
	v_cmp_le_u32_e32 vcc, v165, v48
	s_waitcnt lgkmcnt(0)
	v_mfma_f32_16x16x32_bf16 v[160:163], v[212:215], v[32:35], v[160:163]
	v_max3_f32 v209, v209, v179, v204
	v_cndmask_b32_e32 v208, v198, v166, vcc
	v_cmp_le_u32_e32 vcc, v168, v49
	v_add_u32_e32 v166, 35, v73
	v_mfma_f32_16x16x32_bf16 v[200:203], v[212:215], v[24:27], v[200:203]
	v_cndmask_b32_e32 v210, v198, v156, vcc
	v_cmp_le_u32_e32 vcc, v164, v49
	v_add_u32_e32 v170, 49, v73
	v_max3_f32 v137, v99, s5, v105
	v_cndmask_b32_e32 v211, v198, v157, vcc
	v_cmp_le_u32_e32 vcc, v165, v49
	v_max3_f32 v156, v209, v210, v211
	v_max3_f32 v137, v137, v139, v149
	v_cndmask_b32_e32 v209, v198, v158, vcc
	v_cmp_le_u32_e32 vcc, v166, v49
	v_add_u32_e32 v171, 50, v73
	v_max3_f32 v137, v137, v75, v178
	v_cndmask_b32_e32 v212, v198, v159, vcc
	v_cmp_le_u32_e32 vcc, v166, v48
	v_max3_f32 v137, v137, v199, v205
	v_add_u32_e32 v73, 51, v73
	v_cndmask_b32_e32 v213, v198, v167, vcc
	v_cmp_le_u32_e32 vcc, v169, v49
	v_max3_f32 v137, v137, v206, v207
	v_max3_f32 v137, v137, v208, v213
	v_cndmask_b32_e32 v214, v198, v160, vcc
	v_cmp_le_u32_e32 vcc, v169, v48
	v_max3_f32 v156, v156, v209, v212
	s_nop 0
	v_cndmask_b32_e32 v200, v198, v200, vcc
	v_cmp_le_u32_e32 vcc, v170, v49
	s_nop 1
	v_cndmask_b32_e32 v215, v198, v161, vcc
	v_cmp_le_u32_e32 vcc, v170, v48
	v_max3_f32 v156, v156, v214, v215
	s_nop 0
	v_cndmask_b32_e32 v201, v198, v201, vcc
	v_cmp_le_u32_e32 vcc, v171, v49
	v_max3_f32 v137, v137, v200, v201
	s_nop 0
	v_cndmask_b32_e32 v228, v198, v162, vcc
	v_cmp_le_u32_e32 vcc, v171, v48
	s_nop 1
	v_cndmask_b32_e32 v202, v198, v202, vcc
	v_cmp_le_u32_e32 vcc, v73, v49
	s_nop 1
	v_cndmask_b32_e32 v230, v198, v163, vcc
	v_cmp_le_u32_e32 vcc, v73, v48
	v_max3_f32 v156, v156, v228, v230
	s_nop 0
	v_cndmask_b32_e32 v73, v198, v203, vcc
	v_max3_f32 v137, v137, v202, v73
	v_mov_b32_e32 v157, v137
	v_mov_b32_e32 v158, v137
	s_nop 1
	v_permlane16_swap_b32_e32 v157, v158
	v_cndmask_b32_e64 v157, v157, v158, s[8:9]
	v_max_f32_e32 v157, v157, v157
	v_max_f32_e32 v137, v137, v157
	v_mov_b32_e32 v157, v156
	v_mov_b32_e32 v158, v156
	s_nop 1
	v_permlane16_swap_b32_e32 v157, v158
	v_cndmask_b32_e64 v157, v157, v158, s[8:9]
	v_max_f32_e32 v157, v157, v157
	v_max_f32_e32 v157, v156, v157
	v_mov_b32_e32 v156, v137
	v_mov_b32_e32 v158, v137
	s_nop 1
	v_permlane32_swap_b32_e32 v156, v158
	v_cndmask_b32_e64 v156, v156, v158, s[10:11]
	v_mov_b32_e32 v158, v157
	v_mov_b32_e32 v159, v157
	s_nop 1
	v_permlane32_swap_b32_e32 v158, v159
	v_cndmask_b32_e64 v158, v158, v159, s[10:11]
	v_max3_f32 v232, v69, v157, v158
	v_sub_f32_e32 v69, v69, v232
	v_exp_f32_e32 v157, v69
	v_sub_f32_e32 v69, v95, v232
	v_exp_f32_e32 v69, v69
	v_max3_f32 v137, v71, v137, v156
	v_sub_f32_e32 v71, v71, v137
	v_exp_f32_e32 v156, v71
	v_sub_f32_e32 v71, v99, v137
	v_cmp_lt_f32_e32 vcc, s22, v95
	v_exp_f32_e32 v71, v71
	v_pk_mul_f32 v[42:43], v[42:43], v[156:157] op_sel_hi:[1,0]
	v_cndmask_b32_e32 v159, 0, v69, vcc
	v_sub_f32_e32 v69, v103, v232
	v_exp_f32_e32 v69, v69
	v_cmp_lt_f32_e32 vcc, s22, v99
	v_pk_mul_f32 v[40:41], v[40:41], v[156:157] op_sel_hi:[1,0]
	v_add_u32_e32 v95, 0x4000, v65
	v_cndmask_b32_e32 v158, 0, v71, vcc
	v_sub_f32_e32 v71, v105, v137
	v_cmp_lt_f32_e32 vcc, s22, v103
	v_exp_f32_e32 v71, v71
	v_pk_add_f32 v[162:163], v[158:159], 0 op_sel_hi:[1,0]
	v_cndmask_b32_e32 v161, 0, v69, vcc
	v_sub_f32_e32 v69, v141, v232
	v_exp_f32_e32 v69, v69
	v_cmp_lt_f32_e32 vcc, s22, v105
	v_pk_mul_f32 v[46:47], v[46:47], v[156:157] op_sel_hi:[1,0]
	v_pk_mul_f32 v[44:45], v[44:45], v[156:157] op_sel_hi:[1,0]
	v_cndmask_b32_e32 v160, 0, v71, vcc
	v_sub_f32_e32 v71, v139, v137
	v_cmp_lt_f32_e32 vcc, s22, v141
	v_pk_add_f32 v[164:165], v[160:161], v[162:163]
	v_exp_f32_e32 v71, v71
	v_cndmask_b32_e32 v163, 0, v69, vcc
	v_sub_f32_e32 v69, v153, v232
	v_exp_f32_e32 v69, v69
	v_cmp_lt_f32_e32 vcc, s22, v139
	v_pk_mul_f32 v[38:39], v[38:39], v[156:157] op_sel_hi:[1,0]
	v_pk_mul_f32 v[36:37], v[36:37], v[156:157] op_sel_hi:[1,0]
	v_cndmask_b32_e32 v162, 0, v71, vcc
	v_sub_f32_e32 v71, v149, v137
	v_cmp_lt_f32_e32 vcc, s22, v153
	v_pk_add_f32 v[166:167], v[162:163], v[164:165]
	v_exp_f32_e32 v71, v71
	v_cndmask_b32_e32 v165, 0, v69, vcc
	v_sub_f32_e32 v69, v172, v232
	v_exp_f32_e32 v69, v69
	v_cmp_lt_f32_e32 vcc, s22, v149
	v_pk_mul_f32 v[18:19], v[18:19], v[156:157] op_sel_hi:[1,0]
	v_pk_mul_f32 v[16:17], v[16:17], v[156:157] op_sel_hi:[1,0]
	v_cndmask_b32_e32 v164, 0, v71, vcc
	v_sub_f32_e32 v71, v75, v137
	v_cmp_lt_f32_e32 vcc, s22, v172
	v_pk_add_f32 v[168:169], v[164:165], v[166:167]
	v_exp_f32_e32 v71, v71
	v_cndmask_b32_e32 v167, 0, v69, vcc
	v_sub_f32_e32 v69, v173, v232
	v_exp_f32_e32 v69, v69
	v_cmp_lt_f32_e32 vcc, s22, v75
	s_nop 1
	v_cndmask_b32_e32 v166, 0, v71, vcc
	v_sub_f32_e32 v71, v178, v137
	v_cmp_lt_f32_e32 vcc, s22, v173
	v_pk_add_f32 v[170:171], v[166:167], v[168:169]
	v_exp_f32_e32 v71, v71
	v_cndmask_b32_e32 v169, 0, v69, vcc
	v_sub_f32_e32 v69, v179, v232
	v_exp_f32_e32 v69, v69
	v_cmp_lt_f32_e32 vcc, s22, v178
	s_nop 1
	v_cndmask_b32_e32 v168, 0, v71, vcc
	v_sub_f32_e32 v71, v199, v137
	v_cmp_lt_f32_e32 vcc, s22, v179
	v_pk_add_f32 v[172:173], v[168:169], v[170:171]
	v_exp_f32_e32 v71, v71
	v_cndmask_b32_e32 v171, 0, v69, vcc
	v_sub_f32_e32 v69, v204, v232
	v_exp_f32_e32 v69, v69
	v_cmp_lt_f32_e32 vcc, s22, v199
	s_nop 1
	v_cndmask_b32_e32 v170, 0, v71, vcc
	v_sub_f32_e32 v71, v205, v137
	v_cmp_lt_f32_e32 vcc, s22, v204
	v_pk_add_f32 v[178:179], v[170:171], v[172:173]
	v_exp_f32_e32 v71, v71
	v_cndmask_b32_e32 v173, 0, v69, vcc
	v_sub_f32_e32 v69, v206, v137
	v_exp_f32_e32 v69, v69
	v_cmp_lt_f32_e32 vcc, s22, v205
	s_nop 1
	v_cndmask_b32_e32 v172, 0, v71, vcc
	v_sub_f32_e32 v71, v210, v232
	v_cmp_lt_f32_e32 vcc, s22, v206
	v_exp_f32_e32 v71, v71
	v_pk_add_f32 v[178:179], v[172:173], v[178:179]
	v_cndmask_b32_e32 v216, 0, v69, vcc
	v_sub_f32_e32 v69, v211, v232
	v_exp_f32_e32 v69, v69
	v_cmp_lt_f32_e32 vcc, s22, v210
	v_cvt_pk_bf16_f32 v203, v170, v172
	s_nop 0
	v_cndmask_b32_e32 v217, 0, v71, vcc
	v_sub_f32_e32 v71, v207, v137
	v_cmp_lt_f32_e32 vcc, s22, v211
	v_exp_f32_e32 v71, v71
	v_pk_add_f32 v[178:179], v[216:217], v[178:179]
	v_cndmask_b32_e32 v219, 0, v69, vcc
	v_sub_f32_e32 v69, v209, v232
	v_exp_f32_e32 v69, v69
	v_cmp_lt_f32_e32 vcc, s22, v207
	s_nop 1
	v_cndmask_b32_e32 v218, 0, v71, vcc
	v_sub_f32_e32 v71, v208, v137
	v_cmp_lt_f32_e32 vcc, s22, v209
	v_exp_f32_e32 v71, v71
	v_cvt_pk_bf16_f32 v204, v216, v218
	v_cndmask_b32_e32 v221, 0, v69, vcc
	v_sub_f32_e32 v69, v212, v232
	v_exp_f32_e32 v69, v69
	v_cmp_lt_f32_e32 vcc, s22, v208
	v_mov_b32_e32 v216, v157
	v_pk_add_f32 v[178:179], v[218:219], v[178:179]
	v_cndmask_b32_e32 v220, 0, v71, vcc
	v_sub_f32_e32 v71, v213, v137
	v_cmp_lt_f32_e32 vcc, s22, v212
	v_exp_f32_e32 v71, v71
	ds_read2_b64 v[208:211], v65 offset1:4
	v_cndmask_b32_e32 v223, 0, v69, vcc
	v_sub_f32_e32 v69, v214, v232
	v_exp_f32_e32 v69, v69
	v_cmp_lt_f32_e32 vcc, s22, v213
	v_pk_mul_f32 v[10:11], v[10:11], v[216:217] op_sel_hi:[1,0]
	v_pk_mul_f32 v[8:9], v[8:9], v[216:217] op_sel_hi:[1,0]
	v_cndmask_b32_e32 v222, 0, v71, vcc
	v_sub_f32_e32 v71, v200, v137
	v_cmp_lt_f32_e32 vcc, s22, v214
	v_exp_f32_e32 v71, v71
	v_pk_add_f32 v[178:179], v[220:221], v[178:179]
	v_cndmask_b32_e32 v225, 0, v69, vcc
	v_sub_f32_e32 v69, v215, v232
	v_exp_f32_e32 v69, v69
	v_cmp_lt_f32_e32 vcc, s22, v200
	v_cvt_pk_bf16_f32 v200, v158, v160
	v_cvt_pk_bf16_f32 v160, v167, v169
	v_cndmask_b32_e32 v224, 0, v71, vcc
	v_sub_f32_e32 v71, v201, v137
	v_cmp_lt_f32_e32 vcc, s22, v215
	v_exp_f32_e32 v71, v71
	v_cvt_pk_bf16_f32 v158, v159, v161
	v_cndmask_b32_e32 v227, 0, v69, vcc
	v_sub_f32_e32 v69, v228, v232
	v_exp_f32_e32 v69, v69
	v_cmp_lt_f32_e32 vcc, s22, v201
	v_cvt_pk_bf16_f32 v161, v171, v173
	v_cvt_pk_bf16_f32 v201, v162, v164
	v_cndmask_b32_e32 v226, 0, v71, vcc
	v_sub_f32_e32 v71, v202, v137
	v_cmp_lt_f32_e32 vcc, s22, v228
	v_exp_f32_e32 v71, v71
	v_cvt_pk_bf16_f32 v159, v163, v165
	v_cndmask_b32_e32 v229, 0, v69, vcc
	v_sub_f32_e32 v69, v230, v232
	v_exp_f32_e32 v69, v69
	v_cmp_lt_f32_e32 vcc, s22, v202
	v_cvt_pk_bf16_f32 v202, v166, v168
	v_pk_add_f32 v[178:179], v[222:223], v[178:179]
	v_cndmask_b32_e32 v228, 0, v71, vcc
	v_cmp_lt_f32_e32 vcc, s22, v230
	v_sub_f32_e32 v71, v73, v137
	v_exp_f32_e32 v71, v71
	v_cndmask_b32_e32 v231, 0, v69, vcc
	v_cmp_lt_f32_e32 vcc, s22, v73
	v_add_u32_e32 v73, 0x2000, v65
	ds_read2_b64 v[166:169], v73 offset0:32 offset1:36
	ds_read2_b64 v[170:173], v73 offset0:40 offset1:44
	s_waitcnt lgkmcnt(1)
	v_mfma_f32_16x16x32_bf16 v[40:43], v[166:169], v[200:203], v[40:43]
	v_add_f32_e64 v178, v224, v178
	v_add_f32_e64 v179, v225, v179
	v_cndmask_b32_e32 v230, 0, v71, vcc
	v_pk_add_f32 v[178:179], v[226:227], v[178:179]
	v_mfma_f32_16x16x32_bf16 v[8:11], v[166:169], v[158:161], v[8:11]
	ds_read2_b64 v[166:169], v95 offset0:64 offset1:68
	v_cvt_pk_bf16_f32 v205, v220, v222
	v_cvt_pk_bf16_f32 v206, v224, v226
	v_cvt_pk_bf16_f32 v207, v228, v230
	v_cvt_pk_bf16_f32 v162, v217, v219
	v_cvt_pk_bf16_f32 v163, v221, v223
	v_cvt_pk_bf16_f32 v164, v225, v227
	v_cvt_pk_bf16_f32 v165, v229, v231
	v_pk_add_f32 v[178:179], v[228:229], v[178:179]
	s_waitcnt lgkmcnt(1)
	v_mfma_f32_16x16x32_bf16 v[40:43], v[170:173], v[204:207], v[40:43]
	v_add_f32_e64 v178, v230, v178
	v_add_f32_e64 v179, v231, v179
	v_pk_mul_f32 v[14:15], v[14:15], v[216:217] op_sel_hi:[1,0]
	v_mov_b32_e32 v75, v179
	v_mfma_f32_16x16x32_bf16 v[8:11], v[170:173], v[162:165], v[8:11]
	ds_read2_b64 v[170:173], v95 offset0:72 offset1:76
	v_mov_b32_e32 v73, v179
	v_pk_mul_f32 v[12:13], v[12:13], v[216:217] op_sel_hi:[1,0]
	s_nop 0
	v_permlane16_swap_b32_e32 v75, v73
	v_mfma_f32_16x16x32_bf16 v[44:47], v[208:211], v[200:203], v[44:47]
	v_mul_f32_e64 v6, v6, v216
	v_mul_f32_e64 v7, v7, v216
	v_pk_mul_f32 v[4:5], v[4:5], v[216:217] op_sel_hi:[1,0]
	ds_read2_b64 v[212:215], v65 offset0:8 offset1:12
	v_mfma_f32_16x16x32_bf16 v[12:15], v[208:211], v[158:161], v[12:15]
	v_cndmask_b32_e64 v209, v75, v73, s[8:9]
	v_add_u32_e32 v73, 0x6000, v65
	v_mov_b32_e32 v69, v178
	s_waitcnt lgkmcnt(2)
	v_mfma_f32_16x16x32_bf16 v[36:39], v[166:169], v[200:203], v[36:39]
	v_mov_b32_e32 v71, v178
	v_pk_mul_f32 v[2:3], v[2:3], v[216:217] op_sel_hi:[1,0]
	v_pk_mul_f32 v[0:1], v[0:1], v[216:217] op_sel_hi:[1,0]
	v_mfma_f32_16x16x32_bf16 v[4:7], v[166:169], v[158:161], v[4:7]
	ds_read2_b64 v[166:169], v73 offset0:96 offset1:100
	v_permlane16_swap_b32_e32 v69, v71
	s_waitcnt lgkmcnt(2)
	v_mfma_f32_16x16x32_bf16 v[36:39], v[170:173], v[204:207], v[36:39]
	v_cndmask_b32_e64 v208, v69, v71, s[8:9]
	v_pk_add_f32 v[178:179], v[178:179], v[208:209]
	v_mfma_f32_16x16x32_bf16 v[4:7], v[170:173], v[162:165], v[4:7]
	ds_read2_b64 v[170:173], v73 offset0:104 offset1:108
	v_mov_b32_e32 v69, v178
	v_mov_b32_e32 v71, v178
	s_waitcnt lgkmcnt(1)
	v_mfma_f32_16x16x32_bf16 v[16:19], v[166:169], v[200:203], v[16:19]
	v_mov_b32_e32 v75, v179
	v_mov_b32_e32 v73, v179
	v_permlane32_swap_b32_e32 v69, v71
	v_mfma_f32_16x16x32_bf16 v[0:3], v[166:169], v[158:161], v[0:3]
	v_permlane32_swap_b32_e32 v75, v73
	v_cndmask_b32_e64 v159, v75, v73, s[10:11]
	v_mfma_f32_16x16x32_bf16 v[44:47], v[212:215], v[204:207], v[44:47]
	v_cndmask_b32_e64 v158, v69, v71, s[10:11]
	v_pk_add_f32 v[158:159], v[178:179], v[158:159]
	v_mov_b32_e32 v71, v137
	v_mfma_f32_16x16x32_bf16 v[12:15], v[212:215], v[162:165], v[12:15]
	v_fma_f32 v114, v114, v156, v158
	v_fma_f32 v115, v115, v157, v159
	v_mov_b32_e32 v69, v232
	s_waitcnt lgkmcnt(0)
	v_mfma_f32_16x16x32_bf16 v[16:19], v[170:173], v[204:207], v[16:19]
	v_mfma_f32_16x16x32_bf16 v[0:3], v[170:173], v[162:165], v[0:3]
	s_branch .LBB0_291
